# GEMM k-loop: first 6 MFMAs of every phase issued before the hand-off barrier
# speedup vs baseline: 1.0015x; 1.0015x over previous
; #define PG8_STAGE(bufoff, gbase, voff) do { _Pragma("unroll") for (int _i = 0; _i < 2; ++_i) \
;         __builtin_amdgcn_global_load_lds((const unsigned*)((const char*)(gbase) + (voff)[_i]), (LAS unsigned*)(lds + (bufoff) + ldsw + _i * 8192), 16, 0, 0); } while (0)
; #define PG8_LDA(dst, b, h) do { _Pragma("unroll") for (int m = 0; m < 4; ++m) _Pragma("unroll") for (int k = 0; k < 2; ++k) dst[m][k] = *(const LAS bf16x8*)(lds + PG8_SA(b, h) + aoff + m * 2048 + k * 1024); } while (0)
; #define PG8_LDB(dst, b, h) do { _Pragma("unroll") for (int n = 0; n < 2; ++n) _Pragma("unroll") for (int k = 0; k < 2; ++k) dst[n][k] = *(const LAS bf16x8*)(lds + PG8_SB(b, h) + boff + n * 2048 + k * 1024); } while (0)
; #define PG8_MMA(ai, bj, At, Bt) do { __builtin_amdgcn_s_setprio(1); _Pragma("unroll") for (int m = 0; m < 4; ++m) _Pragma("unroll") for (int n = 0; n < 2; ++n) _Pragma("unroll") for (int k = 0; k < 2; ++k) \
;         acc[ai][bj][m][n] = __builtin_amdgcn_mfma_f32_16x16x32_bf16(Bt[n][k], At[m][k], acc[ai][bj][m][n], 0, 0, 0); __builtin_amdgcn_s_setprio(0); } while (0)
; #define PG8_WAIT_V(n) asm volatile("s_waitcnt vmcnt(" #n ")" ::: "memory")
; #define PG8_WAIT_L(n) asm volatile("s_waitcnt lgkmcnt(" #n ")" ::: "memory")
; #define PG8_BAR __builtin_amdgcn_s_barrier()
; #define PG8_SCHED __builtin_amdgcn_sched_barrier(0)
; template <class Epi>
; __device__ __forceinline__ void gemm_phase(LAS unsigned char* lds, const Gemm g, const StaticOrder& S, const Epi& E) {
;     ...
;         for (int t = 0; t < nt; t += 2) {
;             const bool last = (t == nt - 2);
;             const char* a1 = cA + (size_t)(t + 1) * kstep;
;             const char* a2 = last ? nA : cA + (size_t)(t + 2) * kstep; const char* b2 = last ? nB : cB + (size_t)(t + 2) * kstep;
;             const char* a3 = a2 + kstep; const char* b3 = b2 + kstep;
;             PG8_LDB(B0, 0, 0); PG8_LDB(B1, 0, 1); PG8_SCHED; PG8_LDA(At, 0, 0); PG8_STAGE(PG8_SA(1, 1), a1 + hstep, voffA);
;             PG8_WAIT_V(8); PG8_WAIT_L(0); PG8_BAR; PG8_MMA(0, 0, At, B0); PG8_MMA(0, 1, At, B1); PG8_BAR; PG8_SCHED;
;             PG8_LDA(At, 0, 1); PG8_STAGE(PG8_SB(0, 0), b2, voffB); PG8_STAGE(PG8_SB(0, 1), b2 + hstep, voffB); PG8_STAGE(PG8_SA(0, 0), a2, voffA);
;             PG8_WAIT_V(8); PG8_WAIT_L(0); PG8_BAR; PG8_MMA(1, 0, At, B0); PG8_MMA(1, 1, At, B1); PG8_BAR; PG8_SCHED;
.LBB0_221:
	s_add_u32 s0, s6, 0x80
	s_addc_u32 s1, s7, 0
	s_add_u32 s6, s4, 0x100
	s_addc_u32 s7, s5, 0
	s_mov_b32 s4, 0
	s_waitcnt vmcnt(0)
	s_add_i32 s71, s4, 2
	s_add_u32 s72, s0, 0x80
	s_addc_u32 s5, s1, 0
	s_add_i32 s74, 0, 0x10000
	s_cmp_eq_u32 s62, s4
	s_cselect_b32 s5, s49, s5
	s_cselect_b32 s4, s48, s72
	s_cselect_b32 s73, s51, s7
	s_cselect_b32 s72, s50, s6
	s_add_i32 s75, 0, 0x14000
	v_add_u32_e32 v140, s74, v245
	v_add_u32_e32 v156, s75, v245
	ds_read_b128 v[128:131], v140
	ds_read_b128 v[132:135], v140 offset:1024
	ds_read_b128 v[136:139], v140 offset:2048
	ds_read_b128 v[140:143], v140 offset:3072
	ds_read_b128 v[144:147], v156
	ds_read_b128 v[148:151], v156 offset:1024
	ds_read_b128 v[152:155], v156 offset:2048
	ds_read_b128 v[156:159], v156 offset:3072
	v_lshl_add_u64 v[212:213], s[0:1], 0, v[208:209]
	s_add_i32 m0, s55, 0xc000
	ds_read_b128 v[160:163], v247
	ds_read_b128 v[164:167], v247 offset:1024
	ds_read_b128 v[168:171], v247 offset:2048
	ds_read_b128 v[172:175], v247 offset:3072
	ds_read_b128 v[176:179], v247 offset:4096
	ds_read_b128 v[180:183], v247 offset:5120
	ds_read_b128 v[184:187], v247 offset:6144
	ds_read_b128 v[188:191], v247 offset:7168
	global_load_lds_dwordx4 v[212:213], off
	v_lshl_add_u64 v[212:213], s[0:1], 0, v[210:211]
	s_add_i32 m0, s55, 0xe000
	s_nop 0
	global_load_lds_dwordx4 v[212:213], off
	s_waitcnt vmcnt(8)
	s_waitcnt lgkmcnt(0)
	v_mfma_f32_16x16x32_bf16 v[124:127], v[128:131], v[160:163], 0
	v_mfma_f32_16x16x32_bf16 v[120:123], v[136:139], v[160:163], 0
	v_mfma_f32_16x16x32_bf16 v[108:111], v[128:131], v[168:171], 0
	v_mfma_f32_16x16x32_bf16 v[104:107], v[136:139], v[168:171], 0
	v_mfma_f32_16x16x32_bf16 v[92:95], v[128:131], v[176:179], 0
	v_mfma_f32_16x16x32_bf16 v[88:91], v[136:139], v[176:179], 0
	s_barrier
	s_setprio 1
	s_waitcnt lgkmcnt(0)
	v_mfma_f32_16x16x32_bf16 v[76:79], v[128:131], v[184:187], 0
	v_mfma_f32_16x16x32_bf16 v[72:75], v[136:139], v[184:187], 0
	v_mfma_f32_16x16x32_bf16 v[124:127], v[132:135], v[164:167], v[124:127]
	v_mfma_f32_16x16x32_bf16 v[120:123], v[140:143], v[164:167], v[120:123]
	v_mfma_f32_16x16x32_bf16 v[108:111], v[132:135], v[172:175], v[108:111]
	v_mfma_f32_16x16x32_bf16 v[104:107], v[140:143], v[172:175], v[104:107]
	v_mfma_f32_16x16x32_bf16 v[92:95], v[132:135], v[180:183], v[92:95]
	v_mfma_f32_16x16x32_bf16 v[88:91], v[140:143], v[180:183], v[88:91]
	v_mfma_f32_16x16x32_bf16 v[76:79], v[132:135], v[188:191], v[76:79]
	v_mfma_f32_16x16x32_bf16 v[72:75], v[140:143], v[188:191], v[72:75]
	s_setprio 0
	s_setprio 1
	v_mfma_f32_16x16x32_bf16 v[116:119], v[144:147], v[160:163], 0
	v_mfma_f32_16x16x32_bf16 v[112:115], v[152:155], v[160:163], 0
	v_mfma_f32_16x16x32_bf16 v[100:103], v[144:147], v[168:171], 0
	v_mfma_f32_16x16x32_bf16 v[96:99], v[152:155], v[168:171], 0
	v_mfma_f32_16x16x32_bf16 v[84:87], v[144:147], v[176:179], 0
	v_mfma_f32_16x16x32_bf16 v[80:83], v[152:155], v[176:179], 0
	v_mfma_f32_16x16x32_bf16 v[68:71], v[144:147], v[184:187], 0
	v_mfma_f32_16x16x32_bf16 v[64:67], v[152:155], v[184:187], 0
	v_mfma_f32_16x16x32_bf16 v[116:119], v[148:151], v[164:167], v[116:119]
	v_mfma_f32_16x16x32_bf16 v[112:115], v[156:159], v[164:167], v[112:115]
	v_mfma_f32_16x16x32_bf16 v[100:103], v[148:151], v[172:175], v[100:103]
	v_mfma_f32_16x16x32_bf16 v[96:99], v[156:159], v[172:175], v[96:99]
	v_mfma_f32_16x16x32_bf16 v[84:87], v[148:151], v[180:183], v[84:87]
	v_mfma_f32_16x16x32_bf16 v[80:83], v[156:159], v[180:183], v[80:83]
	v_mfma_f32_16x16x32_bf16 v[68:71], v[148:151], v[188:191], v[68:71]
	v_mfma_f32_16x16x32_bf16 v[64:67], v[156:159], v[188:191], v[64:67]
	s_setprio 0
	s_barrier
	s_add_i32 s74, s74, s54
	v_lshl_add_u64 v[212:213], s[72:73], 0, v[192:193]
	s_mov_b32 m0, s74
	ds_read_b128 v[160:163], v247 offset:16384
	ds_read_b128 v[164:167], v247 offset:17408
	ds_read_b128 v[168:171], v247 offset:18432
	ds_read_b128 v[172:175], v247 offset:19456
	ds_read_b128 v[176:179], v247 offset:20480
	ds_read_b128 v[180:183], v247 offset:21504
	ds_read_b128 v[184:187], v247 offset:22528
	ds_read_b128 v[188:191], v247 offset:23552
	global_load_lds_dwordx4 v[212:213], off
	s_add_i32 m0, s74, 0x2000
	v_lshl_add_u64 v[214:215], s[72:73], 0, v[204:205]
	s_add_u32 s72, s72, s2
	s_addc_u32 s73, s73, 0
	s_add_i32 s74, s75, s54
	global_load_lds_dwordx4 v[214:215], off
	v_lshl_add_u64 v[216:217], s[72:73], 0, v[192:193]
	s_mov_b32 m0, s74
	v_lshl_add_u64 v[218:219], s[72:73], 0, v[204:205]
	global_load_lds_dwordx4 v[216:217], off
	s_add_i32 m0, s74, 0x2000
	v_lshl_add_u64 v[220:221], s[4:5], 0, v[200:201]
	global_load_lds_dwordx4 v[218:219], off
	s_mov_b32 m0, s55
	v_lshl_add_u64 v[222:223], s[4:5], 0, v[202:203]
	global_load_lds_dwordx4 v[220:221], off
	s_mov_b32 m0, s56
	s_nop 0
	global_load_lds_dwordx4 v[222:223], off
	s_waitcnt vmcnt(8)
	s_waitcnt lgkmcnt(0)
	v_mfma_f32_16x16x32_bf16 v[60:63], v[128:131], v[160:163], 0
	v_mfma_f32_16x16x32_bf16 v[56:59], v[136:139], v[160:163], 0
	v_mfma_f32_16x16x32_bf16 v[44:47], v[128:131], v[168:171], 0
	v_mfma_f32_16x16x32_bf16 v[40:43], v[136:139], v[168:171], 0
	v_mfma_f32_16x16x32_bf16 v[28:31], v[128:131], v[176:179], 0
	v_mfma_f32_16x16x32_bf16 v[24:27], v[136:139], v[176:179], 0
	s_barrier
; #define PG8_STAGE(bufoff, gbase, voff) do { _Pragma("unroll") for (int _i = 0; _i < 2; ++_i) \
;         __builtin_amdgcn_global_load_lds((const unsigned*)((const char*)(gbase) + (voff)[_i]), (LAS unsigned*)(lds + (bufoff) + ldsw + _i * 8192), 16, 0, 0); } while (0)
; #define PG8_LDA(dst, b, h) do { _Pragma("unroll") for (int m = 0; m < 4; ++m) _Pragma("unroll") for (int k = 0; k < 2; ++k) dst[m][k] = *(const LAS bf16x8*)(lds + PG8_SA(b, h) + aoff + m * 2048 + k * 1024); } while (0)
; #define PG8_LDB(dst, b, h) do { _Pragma("unroll") for (int n = 0; n < 2; ++n) _Pragma("unroll") for (int k = 0; k < 2; ++k) dst[n][k] = *(const LAS bf16x8*)(lds + PG8_SB(b, h) + boff + n * 2048 + k * 1024); } while (0)
; #define PG8_MMA(ai, bj, At, Bt) do { __builtin_amdgcn_s_setprio(1); _Pragma("unroll") for (int m = 0; m < 4; ++m) _Pragma("unroll") for (int n = 0; n < 2; ++n) _Pragma("unroll") for (int k = 0; k < 2; ++k) \
;         acc[ai][bj][m][n] = __builtin_amdgcn_mfma_f32_16x16x32_bf16(Bt[n][k], At[m][k], acc[ai][bj][m][n], 0, 0, 0); __builtin_amdgcn_s_setprio(0); } while (0)
; #define PG8_WAIT_V(n) asm volatile("s_waitcnt vmcnt(" #n ")" ::: "memory")
; #define PG8_WAIT_L(n) asm volatile("s_waitcnt lgkmcnt(" #n ")" ::: "memory")
; #define PG8_BAR __builtin_amdgcn_s_barrier()
; #define PG8_SCHED __builtin_amdgcn_sched_barrier(0)
; template <class Epi>
; __device__ __forceinline__ void gemm_phase(LAS unsigned char* lds, const Gemm g, const StaticOrder& S, const Epi& E) {
;     ...
;             PG8_LDA(At, 0, 1); PG8_STAGE(PG8_SB(0, 0), b2, voffB); PG8_STAGE(PG8_SB(0, 1), b2 + hstep, voffB); PG8_STAGE(PG8_SA(0, 0), a2, voffA);
;             PG8_WAIT_V(8); PG8_WAIT_L(0); PG8_BAR; PG8_MMA(1, 0, At, B0); PG8_MMA(1, 1, At, B1); PG8_BAR; PG8_SCHED;
;             PG8_LDB(B0, 1, 0); PG8_LDB(B1, 1, 1); PG8_SCHED; PG8_LDA(At, 1, 0); PG8_STAGE(PG8_SA(0, 1), a2 + hstep, voffA);
;             PG8_WAIT_V(8); PG8_WAIT_L(0); PG8_BAR; PG8_MMA(0, 0, At, B0); PG8_MMA(0, 1, At, B1); PG8_BAR; PG8_SCHED;
;             PG8_LDA(At, 1, 1); PG8_STAGE(PG8_SB(1, 0), b3, voffB); PG8_STAGE(PG8_SB(1, 1), b3 + hstep, voffB); PG8_STAGE(PG8_SA(1, 0), a3, voffA);
	s_setprio 1
	s_waitcnt lgkmcnt(0)
	v_mfma_f32_16x16x32_bf16 v[12:15], v[128:131], v[184:187], 0
	v_mfma_f32_16x16x32_bf16 v[8:11], v[136:139], v[184:187], 0
	v_mfma_f32_16x16x32_bf16 v[60:63], v[132:135], v[164:167], v[60:63]
	v_mfma_f32_16x16x32_bf16 v[56:59], v[140:143], v[164:167], v[56:59]
	v_mfma_f32_16x16x32_bf16 v[44:47], v[132:135], v[172:175], v[44:47]
	v_mfma_f32_16x16x32_bf16 v[40:43], v[140:143], v[172:175], v[40:43]
	v_mfma_f32_16x16x32_bf16 v[28:31], v[132:135], v[180:183], v[28:31]
	v_mfma_f32_16x16x32_bf16 v[24:27], v[140:143], v[180:183], v[24:27]
	v_mfma_f32_16x16x32_bf16 v[12:15], v[132:135], v[188:191], v[12:15]
	v_mfma_f32_16x16x32_bf16 v[8:11], v[140:143], v[188:191], v[8:11]
	s_setprio 0
	s_setprio 1
	v_mfma_f32_16x16x32_bf16 v[52:55], v[144:147], v[160:163], 0
	v_mfma_f32_16x16x32_bf16 v[48:51], v[152:155], v[160:163], 0
	v_mfma_f32_16x16x32_bf16 v[36:39], v[144:147], v[168:171], 0
	v_mfma_f32_16x16x32_bf16 v[32:35], v[152:155], v[168:171], 0
	v_mfma_f32_16x16x32_bf16 v[20:23], v[144:147], v[176:179], 0
	v_mfma_f32_16x16x32_bf16 v[16:19], v[152:155], v[176:179], 0
	v_mfma_f32_16x16x32_bf16 v[4:7], v[144:147], v[184:187], 0
	v_mfma_f32_16x16x32_bf16 v[0:3], v[152:155], v[184:187], 0
	v_mfma_f32_16x16x32_bf16 v[52:55], v[148:151], v[164:167], v[52:55]
	v_mfma_f32_16x16x32_bf16 v[48:51], v[156:159], v[164:167], v[48:51]
	v_mfma_f32_16x16x32_bf16 v[36:39], v[148:151], v[172:175], v[36:39]
	v_mfma_f32_16x16x32_bf16 v[32:35], v[156:159], v[172:175], v[32:35]
	v_mfma_f32_16x16x32_bf16 v[20:23], v[148:151], v[180:183], v[20:23]
	v_mfma_f32_16x16x32_bf16 v[16:19], v[156:159], v[180:183], v[16:19]
	v_mfma_f32_16x16x32_bf16 v[4:7], v[148:151], v[188:191], v[4:7]
	v_mfma_f32_16x16x32_bf16 v[0:3], v[156:159], v[188:191], v[0:3]
	s_setprio 0
	s_barrier
	s_add_i32 s72, 0, 0x18000
	s_add_i32 s73, 0, 0x1c000
	v_add_u32_e32 v140, s72, v245
	v_add_u32_e32 v156, s73, v245
	ds_read_b128 v[128:131], v140
	ds_read_b128 v[132:135], v140 offset:1024
	ds_read_b128 v[136:139], v140 offset:2048
	ds_read_b128 v[140:143], v140 offset:3072
	ds_read_b128 v[144:147], v156
	ds_read_b128 v[148:151], v156 offset:1024
	ds_read_b128 v[152:155], v156 offset:2048
	ds_read_b128 v[156:159], v156 offset:3072
	s_add_u32 s4, s4, s2
	s_addc_u32 s5, s5, 0
	s_mov_b32 m0, s57
	v_lshl_add_u64 v[224:225], s[4:5], 0, v[200:201]
	ds_read_b128 v[160:163], v247 offset:32768
	ds_read_b128 v[164:167], v247 offset:33792
	ds_read_b128 v[168:171], v247 offset:34816
	ds_read_b128 v[172:175], v247 offset:35840
	ds_read_b128 v[176:179], v247 offset:36864
	ds_read_b128 v[180:183], v247 offset:37888
	ds_read_b128 v[184:187], v247 offset:38912
	ds_read_b128 v[188:191], v247 offset:39936
	global_load_lds_dwordx4 v[224:225], off
	v_lshl_add_u64 v[224:225], s[4:5], 0, v[202:203]
	s_mov_b32 m0, s58
	s_nop 0
	global_load_lds_dwordx4 v[224:225], off
	s_waitcnt vmcnt(8)
	s_waitcnt lgkmcnt(0)
	v_mfma_f32_16x16x32_bf16 v[124:127], v[128:131], v[160:163], v[124:127]
	v_mfma_f32_16x16x32_bf16 v[120:123], v[136:139], v[160:163], v[120:123]
	v_mfma_f32_16x16x32_bf16 v[108:111], v[128:131], v[168:171], v[108:111]
	v_mfma_f32_16x16x32_bf16 v[104:107], v[136:139], v[168:171], v[104:107]
	v_mfma_f32_16x16x32_bf16 v[92:95], v[128:131], v[176:179], v[92:95]
	v_mfma_f32_16x16x32_bf16 v[88:91], v[136:139], v[176:179], v[88:91]
	s_barrier
	s_setprio 1
	s_waitcnt lgkmcnt(0)
	v_mfma_f32_16x16x32_bf16 v[76:79], v[128:131], v[184:187], v[76:79]
	v_mfma_f32_16x16x32_bf16 v[72:75], v[136:139], v[184:187], v[72:75]
	v_mfma_f32_16x16x32_bf16 v[124:127], v[132:135], v[164:167], v[124:127]
	v_mfma_f32_16x16x32_bf16 v[120:123], v[140:143], v[164:167], v[120:123]
	v_mfma_f32_16x16x32_bf16 v[108:111], v[132:135], v[172:175], v[108:111]
	v_mfma_f32_16x16x32_bf16 v[104:107], v[140:143], v[172:175], v[104:107]
	v_mfma_f32_16x16x32_bf16 v[92:95], v[132:135], v[180:183], v[92:95]
	v_mfma_f32_16x16x32_bf16 v[88:91], v[140:143], v[180:183], v[88:91]
	v_mfma_f32_16x16x32_bf16 v[76:79], v[132:135], v[188:191], v[76:79]
	v_mfma_f32_16x16x32_bf16 v[72:75], v[140:143], v[188:191], v[72:75]
	s_setprio 0
	s_setprio 1
	v_mfma_f32_16x16x32_bf16 v[116:119], v[144:147], v[160:163], v[116:119]
	v_mfma_f32_16x16x32_bf16 v[112:115], v[152:155], v[160:163], v[112:115]
	v_mfma_f32_16x16x32_bf16 v[100:103], v[144:147], v[168:171], v[100:103]
	v_mfma_f32_16x16x32_bf16 v[96:99], v[152:155], v[168:171], v[96:99]
	v_mfma_f32_16x16x32_bf16 v[84:87], v[144:147], v[176:179], v[84:87]
	v_mfma_f32_16x16x32_bf16 v[80:83], v[152:155], v[176:179], v[80:83]
	v_mfma_f32_16x16x32_bf16 v[68:71], v[144:147], v[184:187], v[68:71]
	v_mfma_f32_16x16x32_bf16 v[64:67], v[152:155], v[184:187], v[64:67]
	v_mfma_f32_16x16x32_bf16 v[116:119], v[148:151], v[164:167], v[116:119]
	v_mfma_f32_16x16x32_bf16 v[112:115], v[156:159], v[164:167], v[112:115]
	v_mfma_f32_16x16x32_bf16 v[100:103], v[148:151], v[172:175], v[100:103]
	v_mfma_f32_16x16x32_bf16 v[96:99], v[156:159], v[172:175], v[96:99]
	v_mfma_f32_16x16x32_bf16 v[84:87], v[148:151], v[180:183], v[84:87]
	v_mfma_f32_16x16x32_bf16 v[80:83], v[156:159], v[180:183], v[80:83]
	v_mfma_f32_16x16x32_bf16 v[68:71], v[148:151], v[188:191], v[68:71]
	v_mfma_f32_16x16x32_bf16 v[64:67], v[156:159], v[188:191], v[64:67]
	s_setprio 0
	s_barrier
; #define PG8_STAGE(bufoff, gbase, voff) do { _Pragma("unroll") for (int _i = 0; _i < 2; ++_i) \
;         __builtin_amdgcn_global_load_lds((const unsigned*)((const char*)(gbase) + (voff)[_i]), (LAS unsigned*)(lds + (bufoff) + ldsw + _i * 8192), 16, 0, 0); } while (0)
; #define PG8_LDA(dst, b, h) do { _Pragma("unroll") for (int m = 0; m < 4; ++m) _Pragma("unroll") for (int k = 0; k < 2; ++k) dst[m][k] = *(const LAS bf16x8*)(lds + PG8_SA(b, h) + aoff + m * 2048 + k * 1024); } while (0)
; #define PG8_LDB(dst, b, h) do { _Pragma("unroll") for (int n = 0; n < 2; ++n) _Pragma("unroll") for (int k = 0; k < 2; ++k) dst[n][k] = *(const LAS bf16x8*)(lds + PG8_SB(b, h) + boff + n * 2048 + k * 1024); } while (0)
; #define PG8_MMA(ai, bj, At, Bt) do { __builtin_amdgcn_s_setprio(1); _Pragma("unroll") for (int m = 0; m < 4; ++m) _Pragma("unroll") for (int n = 0; n < 2; ++n) _Pragma("unroll") for (int k = 0; k < 2; ++k) \
;         acc[ai][bj][m][n] = __builtin_amdgcn_mfma_f32_16x16x32_bf16(Bt[n][k], At[m][k], acc[ai][bj][m][n], 0, 0, 0); __builtin_amdgcn_s_setprio(0); } while (0)
; #define PG8_WAIT_V(n) asm volatile("s_waitcnt vmcnt(" #n ")" ::: "memory")
; #define PG8_WAIT_L(n) asm volatile("s_waitcnt lgkmcnt(" #n ")" ::: "memory")
; #define PG8_BAR __builtin_amdgcn_s_barrier()
; #define PG8_SCHED __builtin_amdgcn_sched_barrier(0)
; template <class Epi>
; __device__ __forceinline__ void gemm_phase(LAS unsigned char* lds, const Gemm g, const StaticOrder& S, const Epi& E) {
;     ...
;         for (int t = 0; t < nt; t += 2) {
;             const bool last = (t == nt - 2);
;             const char* a1 = cA + (size_t)(t + 1) * kstep;
;             const char* a2 = last ? nA : cA + (size_t)(t + 2) * kstep; const char* b2 = last ? nB : cB + (size_t)(t + 2) * kstep;
;             const char* a3 = a2 + kstep; const char* b3 = b2 + kstep;
;             PG8_LDB(B0, 0, 0); PG8_LDB(B1, 0, 1); PG8_SCHED; PG8_LDA(At, 0, 0); PG8_STAGE(PG8_SA(1, 1), a1 + hstep, voffA);
;             PG8_WAIT_V(8); PG8_WAIT_L(0); PG8_BAR; PG8_MMA(0, 0, At, B0); PG8_MMA(0, 1, At, B1); PG8_BAR; PG8_SCHED;
;     ...
;             PG8_LDA(At, 1, 1); PG8_STAGE(PG8_SB(1, 0), b3, voffB); PG8_STAGE(PG8_SB(1, 1), b3 + hstep, voffB); PG8_STAGE(PG8_SA(1, 0), a3, voffA);
;             PG8_WAIT_V(8); PG8_WAIT_L(0); PG8_BAR; PG8_MMA(1, 0, At, B0); PG8_MMA(1, 1, At, B1); PG8_BAR; PG8_SCHED;
	s_add_i32 s4, s72, s54
	v_lshl_add_u64 v[212:213], v[212:213], 0, s[12:13]
	s_mov_b32 m0, s4
	ds_read_b128 v[160:163], v247 offset:49152
	ds_read_b128 v[164:167], v247 offset:50176
	ds_read_b128 v[168:171], v247 offset:51200
	ds_read_b128 v[172:175], v247 offset:52224
	ds_read_b128 v[176:179], v247 offset:53248
	ds_read_b128 v[180:183], v247 offset:54272
	ds_read_b128 v[184:187], v247 offset:55296
	ds_read_b128 v[188:191], v247 offset:56320
	global_load_lds_dwordx4 v[212:213], off
	v_lshl_add_u64 v[212:213], v[214:215], 0, s[12:13]
	s_add_i32 m0, s4, 0x2000
	s_add_i32 s4, s73, s54
	global_load_lds_dwordx4 v[212:213], off
	v_lshl_add_u64 v[212:213], v[216:217], 0, s[12:13]
	s_mov_b32 m0, s4
	s_nop 0
	global_load_lds_dwordx4 v[212:213], off
	v_lshl_add_u64 v[212:213], v[218:219], 0, s[12:13]
	s_add_i32 m0, s4, 0x2000
	s_nop 0
	global_load_lds_dwordx4 v[212:213], off
	v_lshl_add_u64 v[212:213], v[220:221], 0, s[12:13]
	s_mov_b32 m0, s59
	s_nop 0
	global_load_lds_dwordx4 v[212:213], off
	v_lshl_add_u64 v[212:213], v[222:223], 0, s[12:13]
	s_mov_b32 m0, s60
	s_nop 0
	global_load_lds_dwordx4 v[212:213], off
	s_waitcnt vmcnt(8)
	s_waitcnt lgkmcnt(0)
	v_mfma_f32_16x16x32_bf16 v[60:63], v[128:131], v[160:163], v[60:63]
	v_mfma_f32_16x16x32_bf16 v[56:59], v[136:139], v[160:163], v[56:59]
	v_mfma_f32_16x16x32_bf16 v[44:47], v[128:131], v[168:171], v[44:47]
	v_mfma_f32_16x16x32_bf16 v[40:43], v[136:139], v[168:171], v[40:43]
	v_mfma_f32_16x16x32_bf16 v[28:31], v[128:131], v[176:179], v[28:31]
	v_mfma_f32_16x16x32_bf16 v[24:27], v[136:139], v[176:179], v[24:27]
	s_barrier
	s_setprio 1
	s_waitcnt lgkmcnt(0)
	v_mfma_f32_16x16x32_bf16 v[12:15], v[128:131], v[184:187], v[12:15]
	v_mfma_f32_16x16x32_bf16 v[8:11], v[136:139], v[184:187], v[8:11]
	v_mfma_f32_16x16x32_bf16 v[60:63], v[132:135], v[164:167], v[60:63]
	v_mfma_f32_16x16x32_bf16 v[56:59], v[140:143], v[164:167], v[56:59]
	v_mfma_f32_16x16x32_bf16 v[44:47], v[132:135], v[172:175], v[44:47]
	v_mfma_f32_16x16x32_bf16 v[40:43], v[140:143], v[172:175], v[40:43]
	v_mfma_f32_16x16x32_bf16 v[28:31], v[132:135], v[180:183], v[28:31]
	v_mfma_f32_16x16x32_bf16 v[24:27], v[140:143], v[180:183], v[24:27]
	v_mfma_f32_16x16x32_bf16 v[12:15], v[132:135], v[188:191], v[12:15]
	v_mfma_f32_16x16x32_bf16 v[8:11], v[140:143], v[188:191], v[8:11]
	s_setprio 0
	s_setprio 1
	v_mfma_f32_16x16x32_bf16 v[52:55], v[144:147], v[160:163], v[52:55]
	v_mfma_f32_16x16x32_bf16 v[48:51], v[152:155], v[160:163], v[48:51]
	v_mfma_f32_16x16x32_bf16 v[36:39], v[144:147], v[168:171], v[36:39]
	v_mfma_f32_16x16x32_bf16 v[32:35], v[152:155], v[168:171], v[32:35]
	v_mfma_f32_16x16x32_bf16 v[20:23], v[144:147], v[176:179], v[20:23]
	v_mfma_f32_16x16x32_bf16 v[16:19], v[152:155], v[176:179], v[16:19]
	v_mfma_f32_16x16x32_bf16 v[4:7], v[144:147], v[184:187], v[4:7]
	v_mfma_f32_16x16x32_bf16 v[0:3], v[152:155], v[184:187], v[0:3]
	v_mfma_f32_16x16x32_bf16 v[52:55], v[148:151], v[164:167], v[52:55]
	v_mfma_f32_16x16x32_bf16 v[48:51], v[156:159], v[164:167], v[48:51]
	v_mfma_f32_16x16x32_bf16 v[36:39], v[148:151], v[172:175], v[36:39]
	v_mfma_f32_16x16x32_bf16 v[32:35], v[156:159], v[172:175], v[32:35]
	v_mfma_f32_16x16x32_bf16 v[20:23], v[148:151], v[180:183], v[20:23]
	v_mfma_f32_16x16x32_bf16 v[16:19], v[156:159], v[180:183], v[16:19]
	v_mfma_f32_16x16x32_bf16 v[4:7], v[148:151], v[188:191], v[4:7]
	v_mfma_f32_16x16x32_bf16 v[0:3], v[156:159], v[188:191], v[0:3]
	s_setprio 0
	s_barrier
	s_add_u32 s0, s0, 0x100
	s_addc_u32 s1, s1, 0
	s_add_u32 s6, s6, 0x100
	s_addc_u32 s7, s7, 0
	s_cmp_ge_u32 s71, s61
	s_mov_b32 s4, s71
	s_cbranch_scc1 .Lk_done
.LBB0_222:
	s_add_i32 s71, s4, 2
	s_add_u32 s72, s0, 0x80
	s_addc_u32 s5, s1, 0
	s_add_i32 s74, 0, 0x10000
	s_cmp_eq_u32 s62, s4
	s_cselect_b32 s5, s49, s5
	s_cselect_b32 s4, s48, s72
	s_cselect_b32 s73, s51, s7
	s_cselect_b32 s72, s50, s6
	s_add_i32 s75, 0, 0x14000
	v_add_u32_e32 v140, s74, v245
	v_add_u32_e32 v156, s75, v245
	ds_read_b128 v[128:131], v140
	ds_read_b128 v[132:135], v140 offset:1024
	ds_read_b128 v[136:139], v140 offset:2048
	ds_read_b128 v[140:143], v140 offset:3072
	ds_read_b128 v[144:147], v156
	ds_read_b128 v[148:151], v156 offset:1024
	ds_read_b128 v[152:155], v156 offset:2048
	ds_read_b128 v[156:159], v156 offset:3072
	v_lshl_add_u64 v[212:213], s[0:1], 0, v[208:209]
	s_add_i32 m0, s55, 0xc000
	ds_read_b128 v[160:163], v247
	ds_read_b128 v[164:167], v247 offset:1024
	ds_read_b128 v[168:171], v247 offset:2048
	ds_read_b128 v[172:175], v247 offset:3072
	ds_read_b128 v[176:179], v247 offset:4096
	ds_read_b128 v[180:183], v247 offset:5120
	ds_read_b128 v[184:187], v247 offset:6144
	ds_read_b128 v[188:191], v247 offset:7168
	global_load_lds_dwordx4 v[212:213], off
	v_lshl_add_u64 v[212:213], s[0:1], 0, v[210:211]
	s_add_i32 m0, s55, 0xe000
	s_nop 0
	global_load_lds_dwordx4 v[212:213], off
	s_waitcnt vmcnt(8)
	s_waitcnt lgkmcnt(0)
	v_mfma_f32_16x16x32_bf16 v[124:127], v[128:131], v[160:163], v[124:127]
	v_mfma_f32_16x16x32_bf16 v[120:123], v[136:139], v[160:163], v[120:123]
	v_mfma_f32_16x16x32_bf16 v[108:111], v[128:131], v[168:171], v[108:111]
	v_mfma_f32_16x16x32_bf16 v[104:107], v[136:139], v[168:171], v[104:107]
	v_mfma_f32_16x16x32_bf16 v[92:95], v[128:131], v[176:179], v[92:95]
	v_mfma_f32_16x16x32_bf16 v[88:91], v[136:139], v[176:179], v[88:91]
	s_barrier
; #define PG8_STAGE(bufoff, gbase, voff) do { _Pragma("unroll") for (int _i = 0; _i < 2; ++_i) \
;         __builtin_amdgcn_global_load_lds((const unsigned*)((const char*)(gbase) + (voff)[_i]), (LAS unsigned*)(lds + (bufoff) + ldsw + _i * 8192), 16, 0, 0); } while (0)
; #define PG8_LDA(dst, b, h) do { _Pragma("unroll") for (int m = 0; m < 4; ++m) _Pragma("unroll") for (int k = 0; k < 2; ++k) dst[m][k] = *(const LAS bf16x8*)(lds + PG8_SA(b, h) + aoff + m * 2048 + k * 1024); } while (0)
; #define PG8_MMA(ai, bj, At, Bt) do { __builtin_amdgcn_s_setprio(1); _Pragma("unroll") for (int m = 0; m < 4; ++m) _Pragma("unroll") for (int n = 0; n < 2; ++n) _Pragma("unroll") for (int k = 0; k < 2; ++k) \
;         acc[ai][bj][m][n] = __builtin_amdgcn_mfma_f32_16x16x32_bf16(Bt[n][k], At[m][k], acc[ai][bj][m][n], 0, 0, 0); __builtin_amdgcn_s_setprio(0); } while (0)
; #define PG8_WAIT_V(n) asm volatile("s_waitcnt vmcnt(" #n ")" ::: "memory")
; #define PG8_WAIT_L(n) asm volatile("s_waitcnt lgkmcnt(" #n ")" ::: "memory")
; #define PG8_BAR __builtin_amdgcn_s_barrier()
; #define PG8_SCHED __builtin_amdgcn_sched_barrier(0)
; template <class Epi>
; __device__ __forceinline__ void gemm_phase(LAS unsigned char* lds, const Gemm g, const StaticOrder& S, const Epi& E) {
;     ...
;             PG8_WAIT_V(8); PG8_WAIT_L(0); PG8_BAR; PG8_MMA(0, 0, At, B0); PG8_MMA(0, 1, At, B1); PG8_BAR; PG8_SCHED;
;             PG8_LDA(At, 0, 1); PG8_STAGE(PG8_SB(0, 0), b2, voffB); PG8_STAGE(PG8_SB(0, 1), b2 + hstep, voffB); PG8_STAGE(PG8_SA(0, 0), a2, voffA);
;             PG8_WAIT_V(8); PG8_WAIT_L(0); PG8_BAR; PG8_MMA(1, 0, At, B0); PG8_MMA(1, 1, At, B1); PG8_BAR; PG8_SCHED;
	s_setprio 1
	s_waitcnt lgkmcnt(0)
	v_mfma_f32_16x16x32_bf16 v[76:79], v[128:131], v[184:187], v[76:79]
	v_mfma_f32_16x16x32_bf16 v[72:75], v[136:139], v[184:187], v[72:75]
	v_mfma_f32_16x16x32_bf16 v[124:127], v[132:135], v[164:167], v[124:127]
	v_mfma_f32_16x16x32_bf16 v[120:123], v[140:143], v[164:167], v[120:123]
	v_mfma_f32_16x16x32_bf16 v[108:111], v[132:135], v[172:175], v[108:111]
	v_mfma_f32_16x16x32_bf16 v[104:107], v[140:143], v[172:175], v[104:107]
	v_mfma_f32_16x16x32_bf16 v[92:95], v[132:135], v[180:183], v[92:95]
	v_mfma_f32_16x16x32_bf16 v[88:91], v[140:143], v[180:183], v[88:91]
	v_mfma_f32_16x16x32_bf16 v[76:79], v[132:135], v[188:191], v[76:79]
	v_mfma_f32_16x16x32_bf16 v[72:75], v[140:143], v[188:191], v[72:75]
	s_setprio 0
	s_setprio 1
	v_mfma_f32_16x16x32_bf16 v[116:119], v[144:147], v[160:163], v[116:119]
	v_mfma_f32_16x16x32_bf16 v[112:115], v[152:155], v[160:163], v[112:115]
	v_mfma_f32_16x16x32_bf16 v[100:103], v[144:147], v[168:171], v[100:103]
	v_mfma_f32_16x16x32_bf16 v[96:99], v[152:155], v[168:171], v[96:99]
	v_mfma_f32_16x16x32_bf16 v[84:87], v[144:147], v[176:179], v[84:87]
	v_mfma_f32_16x16x32_bf16 v[80:83], v[152:155], v[176:179], v[80:83]
	v_mfma_f32_16x16x32_bf16 v[68:71], v[144:147], v[184:187], v[68:71]
	v_mfma_f32_16x16x32_bf16 v[64:67], v[152:155], v[184:187], v[64:67]
	v_mfma_f32_16x16x32_bf16 v[116:119], v[148:151], v[164:167], v[116:119]
	v_mfma_f32_16x16x32_bf16 v[112:115], v[156:159], v[164:167], v[112:115]
	v_mfma_f32_16x16x32_bf16 v[100:103], v[148:151], v[172:175], v[100:103]
	v_mfma_f32_16x16x32_bf16 v[96:99], v[156:159], v[172:175], v[96:99]
	v_mfma_f32_16x16x32_bf16 v[84:87], v[148:151], v[180:183], v[84:87]
	v_mfma_f32_16x16x32_bf16 v[80:83], v[156:159], v[180:183], v[80:83]
	v_mfma_f32_16x16x32_bf16 v[68:71], v[148:151], v[188:191], v[68:71]
	v_mfma_f32_16x16x32_bf16 v[64:67], v[156:159], v[188:191], v[64:67]
	s_setprio 0
	s_barrier
	s_add_i32 s74, s74, s54
	v_lshl_add_u64 v[212:213], s[72:73], 0, v[192:193]
	s_mov_b32 m0, s74
	ds_read_b128 v[160:163], v247 offset:16384
	ds_read_b128 v[164:167], v247 offset:17408
	ds_read_b128 v[168:171], v247 offset:18432
	ds_read_b128 v[172:175], v247 offset:19456
	ds_read_b128 v[176:179], v247 offset:20480
	ds_read_b128 v[180:183], v247 offset:21504
	ds_read_b128 v[184:187], v247 offset:22528
	ds_read_b128 v[188:191], v247 offset:23552
	global_load_lds_dwordx4 v[212:213], off
	s_add_i32 m0, s74, 0x2000
	v_lshl_add_u64 v[214:215], s[72:73], 0, v[204:205]
	s_add_u32 s72, s72, s2
	s_addc_u32 s73, s73, 0
	s_add_i32 s74, s75, s54
	global_load_lds_dwordx4 v[214:215], off
	v_lshl_add_u64 v[216:217], s[72:73], 0, v[192:193]
	s_mov_b32 m0, s74
	v_lshl_add_u64 v[218:219], s[72:73], 0, v[204:205]
	global_load_lds_dwordx4 v[216:217], off
	s_add_i32 m0, s74, 0x2000
	v_lshl_add_u64 v[220:221], s[4:5], 0, v[200:201]
	global_load_lds_dwordx4 v[218:219], off
	s_mov_b32 m0, s55
	v_lshl_add_u64 v[222:223], s[4:5], 0, v[202:203]
	global_load_lds_dwordx4 v[220:221], off
	s_mov_b32 m0, s56
	s_nop 0
	global_load_lds_dwordx4 v[222:223], off
	s_waitcnt vmcnt(8)
	s_waitcnt lgkmcnt(0)
	v_mfma_f32_16x16x32_bf16 v[60:63], v[128:131], v[160:163], v[60:63]
	v_mfma_f32_16x16x32_bf16 v[56:59], v[136:139], v[160:163], v[56:59]
	v_mfma_f32_16x16x32_bf16 v[44:47], v[128:131], v[168:171], v[44:47]
	v_mfma_f32_16x16x32_bf16 v[40:43], v[136:139], v[168:171], v[40:43]
	v_mfma_f32_16x16x32_bf16 v[28:31], v[128:131], v[176:179], v[28:31]
	v_mfma_f32_16x16x32_bf16 v[24:27], v[136:139], v[176:179], v[24:27]
	s_barrier
	s_setprio 1
	s_waitcnt lgkmcnt(0)
	v_mfma_f32_16x16x32_bf16 v[12:15], v[128:131], v[184:187], v[12:15]
	v_mfma_f32_16x16x32_bf16 v[8:11], v[136:139], v[184:187], v[8:11]
	v_mfma_f32_16x16x32_bf16 v[60:63], v[132:135], v[164:167], v[60:63]
	v_mfma_f32_16x16x32_bf16 v[56:59], v[140:143], v[164:167], v[56:59]
	v_mfma_f32_16x16x32_bf16 v[44:47], v[132:135], v[172:175], v[44:47]
	v_mfma_f32_16x16x32_bf16 v[40:43], v[140:143], v[172:175], v[40:43]
	v_mfma_f32_16x16x32_bf16 v[28:31], v[132:135], v[180:183], v[28:31]
	v_mfma_f32_16x16x32_bf16 v[24:27], v[140:143], v[180:183], v[24:27]
	v_mfma_f32_16x16x32_bf16 v[12:15], v[132:135], v[188:191], v[12:15]
	v_mfma_f32_16x16x32_bf16 v[8:11], v[140:143], v[188:191], v[8:11]
	s_setprio 0
	s_setprio 1
	v_mfma_f32_16x16x32_bf16 v[52:55], v[144:147], v[160:163], v[52:55]
	v_mfma_f32_16x16x32_bf16 v[48:51], v[152:155], v[160:163], v[48:51]
	v_mfma_f32_16x16x32_bf16 v[36:39], v[144:147], v[168:171], v[36:39]
	v_mfma_f32_16x16x32_bf16 v[32:35], v[152:155], v[168:171], v[32:35]
	v_mfma_f32_16x16x32_bf16 v[20:23], v[144:147], v[176:179], v[20:23]
	v_mfma_f32_16x16x32_bf16 v[16:19], v[152:155], v[176:179], v[16:19]
	v_mfma_f32_16x16x32_bf16 v[4:7], v[144:147], v[184:187], v[4:7]
	v_mfma_f32_16x16x32_bf16 v[0:3], v[152:155], v[184:187], v[0:3]
	v_mfma_f32_16x16x32_bf16 v[52:55], v[148:151], v[164:167], v[52:55]
	v_mfma_f32_16x16x32_bf16 v[48:51], v[156:159], v[164:167], v[48:51]
	v_mfma_f32_16x16x32_bf16 v[36:39], v[148:151], v[172:175], v[36:39]
	v_mfma_f32_16x16x32_bf16 v[32:35], v[156:159], v[172:175], v[32:35]
	v_mfma_f32_16x16x32_bf16 v[20:23], v[148:151], v[180:183], v[20:23]
	v_mfma_f32_16x16x32_bf16 v[16:19], v[156:159], v[180:183], v[16:19]
	v_mfma_f32_16x16x32_bf16 v[4:7], v[148:151], v[188:191], v[4:7]
	v_mfma_f32_16x16x32_bf16 v[0:3], v[156:159], v[188:191], v[0:3]
	s_setprio 0
	s_barrier
; #define PG8_STAGE(bufoff, gbase, voff) do { _Pragma("unroll") for (int _i = 0; _i < 2; ++_i) \
;         __builtin_amdgcn_global_load_lds((const unsigned*)((const char*)(gbase) + (voff)[_i]), (LAS unsigned*)(lds + (bufoff) + ldsw + _i * 8192), 16, 0, 0); } while (0)
; #define PG8_LDA(dst, b, h) do { _Pragma("unroll") for (int m = 0; m < 4; ++m) _Pragma("unroll") for (int k = 0; k < 2; ++k) dst[m][k] = *(const LAS bf16x8*)(lds + PG8_SA(b, h) + aoff + m * 2048 + k * 1024); } while (0)
; #define PG8_LDB(dst, b, h) do { _Pragma("unroll") for (int n = 0; n < 2; ++n) _Pragma("unroll") for (int k = 0; k < 2; ++k) dst[n][k] = *(const LAS bf16x8*)(lds + PG8_SB(b, h) + boff + n * 2048 + k * 1024); } while (0)
; #define PG8_MMA(ai, bj, At, Bt) do { __builtin_amdgcn_s_setprio(1); _Pragma("unroll") for (int m = 0; m < 4; ++m) _Pragma("unroll") for (int n = 0; n < 2; ++n) _Pragma("unroll") for (int k = 0; k < 2; ++k) \
;         acc[ai][bj][m][n] = __builtin_amdgcn_mfma_f32_16x16x32_bf16(Bt[n][k], At[m][k], acc[ai][bj][m][n], 0, 0, 0); __builtin_amdgcn_s_setprio(0); } while (0)
; #define PG8_WAIT_V(n) asm volatile("s_waitcnt vmcnt(" #n ")" ::: "memory")
; #define PG8_WAIT_L(n) asm volatile("s_waitcnt lgkmcnt(" #n ")" ::: "memory")
; #define PG8_BAR __builtin_amdgcn_s_barrier()
; #define PG8_SCHED __builtin_amdgcn_sched_barrier(0)
; template <class Epi>
; __device__ __forceinline__ void gemm_phase(LAS unsigned char* lds, const Gemm g, const StaticOrder& S, const Epi& E) {
;     ...
;             PG8_LDB(B0, 1, 0); PG8_LDB(B1, 1, 1); PG8_SCHED; PG8_LDA(At, 1, 0); PG8_STAGE(PG8_SA(0, 1), a2 + hstep, voffA);
;             PG8_WAIT_V(8); PG8_WAIT_L(0); PG8_BAR; PG8_MMA(0, 0, At, B0); PG8_MMA(0, 1, At, B1); PG8_BAR; PG8_SCHED;
	s_add_i32 s72, 0, 0x18000
	s_add_i32 s73, 0, 0x1c000
	v_add_u32_e32 v140, s72, v245
	v_add_u32_e32 v156, s73, v245
	ds_read_b128 v[128:131], v140
	ds_read_b128 v[132:135], v140 offset:1024
	ds_read_b128 v[136:139], v140 offset:2048
	ds_read_b128 v[140:143], v140 offset:3072
	ds_read_b128 v[144:147], v156
	ds_read_b128 v[148:151], v156 offset:1024
	ds_read_b128 v[152:155], v156 offset:2048
	ds_read_b128 v[156:159], v156 offset:3072
	s_add_u32 s4, s4, s2
	s_addc_u32 s5, s5, 0
	s_mov_b32 m0, s57
	v_lshl_add_u64 v[224:225], s[4:5], 0, v[200:201]
	ds_read_b128 v[160:163], v247 offset:32768
	ds_read_b128 v[164:167], v247 offset:33792
	ds_read_b128 v[168:171], v247 offset:34816
	ds_read_b128 v[172:175], v247 offset:35840
	ds_read_b128 v[176:179], v247 offset:36864
	ds_read_b128 v[180:183], v247 offset:37888
	ds_read_b128 v[184:187], v247 offset:38912
	ds_read_b128 v[188:191], v247 offset:39936
	global_load_lds_dwordx4 v[224:225], off
	v_lshl_add_u64 v[224:225], s[4:5], 0, v[202:203]
	s_mov_b32 m0, s58
	s_nop 0
	global_load_lds_dwordx4 v[224:225], off
	s_waitcnt vmcnt(8)
	s_waitcnt lgkmcnt(0)
	v_mfma_f32_16x16x32_bf16 v[124:127], v[128:131], v[160:163], v[124:127]
	v_mfma_f32_16x16x32_bf16 v[120:123], v[136:139], v[160:163], v[120:123]
	v_mfma_f32_16x16x32_bf16 v[108:111], v[128:131], v[168:171], v[108:111]
	v_mfma_f32_16x16x32_bf16 v[104:107], v[136:139], v[168:171], v[104:107]
	v_mfma_f32_16x16x32_bf16 v[92:95], v[128:131], v[176:179], v[92:95]
	v_mfma_f32_16x16x32_bf16 v[88:91], v[136:139], v[176:179], v[88:91]
	s_barrier
	s_setprio 1
	s_waitcnt lgkmcnt(0)
	v_mfma_f32_16x16x32_bf16 v[76:79], v[128:131], v[184:187], v[76:79]
	v_mfma_f32_16x16x32_bf16 v[72:75], v[136:139], v[184:187], v[72:75]
	v_mfma_f32_16x16x32_bf16 v[124:127], v[132:135], v[164:167], v[124:127]
	v_mfma_f32_16x16x32_bf16 v[120:123], v[140:143], v[164:167], v[120:123]
	v_mfma_f32_16x16x32_bf16 v[108:111], v[132:135], v[172:175], v[108:111]
	v_mfma_f32_16x16x32_bf16 v[104:107], v[140:143], v[172:175], v[104:107]
	v_mfma_f32_16x16x32_bf16 v[92:95], v[132:135], v[180:183], v[92:95]
	v_mfma_f32_16x16x32_bf16 v[88:91], v[140:143], v[180:183], v[88:91]
	v_mfma_f32_16x16x32_bf16 v[76:79], v[132:135], v[188:191], v[76:79]
	v_mfma_f32_16x16x32_bf16 v[72:75], v[140:143], v[188:191], v[72:75]
	s_setprio 0
	s_setprio 1
	v_mfma_f32_16x16x32_bf16 v[116:119], v[144:147], v[160:163], v[116:119]
	v_mfma_f32_16x16x32_bf16 v[112:115], v[152:155], v[160:163], v[112:115]
	v_mfma_f32_16x16x32_bf16 v[100:103], v[144:147], v[168:171], v[100:103]
	v_mfma_f32_16x16x32_bf16 v[96:99], v[152:155], v[168:171], v[96:99]
	v_mfma_f32_16x16x32_bf16 v[84:87], v[144:147], v[176:179], v[84:87]
	v_mfma_f32_16x16x32_bf16 v[80:83], v[152:155], v[176:179], v[80:83]
	v_mfma_f32_16x16x32_bf16 v[68:71], v[144:147], v[184:187], v[68:71]
	v_mfma_f32_16x16x32_bf16 v[64:67], v[152:155], v[184:187], v[64:67]
	v_mfma_f32_16x16x32_bf16 v[116:119], v[148:151], v[164:167], v[116:119]
	v_mfma_f32_16x16x32_bf16 v[112:115], v[156:159], v[164:167], v[112:115]
	v_mfma_f32_16x16x32_bf16 v[100:103], v[148:151], v[172:175], v[100:103]
	v_mfma_f32_16x16x32_bf16 v[96:99], v[156:159], v[172:175], v[96:99]
	v_mfma_f32_16x16x32_bf16 v[84:87], v[148:151], v[180:183], v[84:87]
	v_mfma_f32_16x16x32_bf16 v[80:83], v[156:159], v[180:183], v[80:83]
	v_mfma_f32_16x16x32_bf16 v[68:71], v[148:151], v[188:191], v[68:71]
	v_mfma_f32_16x16x32_bf16 v[64:67], v[156:159], v[188:191], v[64:67]
	s_setprio 0
	s_barrier
; #define PG8_STAGE(bufoff, gbase, voff) do { _Pragma("unroll") for (int _i = 0; _i < 2; ++_i) \
;         __builtin_amdgcn_global_load_lds((const unsigned*)((const char*)(gbase) + (voff)[_i]), (LAS unsigned*)(lds + (bufoff) + ldsw + _i * 8192), 16, 0, 0); } while (0)
; #define PG8_LDA(dst, b, h) do { _Pragma("unroll") for (int m = 0; m < 4; ++m) _Pragma("unroll") for (int k = 0; k < 2; ++k) dst[m][k] = *(const LAS bf16x8*)(lds + PG8_SA(b, h) + aoff + m * 2048 + k * 1024); } while (0)
; #define PG8_MMA(ai, bj, At, Bt) do { __builtin_amdgcn_s_setprio(1); _Pragma("unroll") for (int m = 0; m < 4; ++m) _Pragma("unroll") for (int n = 0; n < 2; ++n) _Pragma("unroll") for (int k = 0; k < 2; ++k) \
;         acc[ai][bj][m][n] = __builtin_amdgcn_mfma_f32_16x16x32_bf16(Bt[n][k], At[m][k], acc[ai][bj][m][n], 0, 0, 0); __builtin_amdgcn_s_setprio(0); } while (0)
; #define PG8_WAIT_V(n) asm volatile("s_waitcnt vmcnt(" #n ")" ::: "memory")
; #define PG8_WAIT_L(n) asm volatile("s_waitcnt lgkmcnt(" #n ")" ::: "memory")
; #define PG8_BAR __builtin_amdgcn_s_barrier()
; #define PG8_SCHED __builtin_amdgcn_sched_barrier(0)
; template <class Epi>
; __device__ __forceinline__ void gemm_phase(LAS unsigned char* lds, const Gemm g, const StaticOrder& S, const Epi& E) {
;     ...
;             PG8_LDA(At, 1, 1); PG8_STAGE(PG8_SB(1, 0), b3, voffB); PG8_STAGE(PG8_SB(1, 1), b3 + hstep, voffB); PG8_STAGE(PG8_SA(1, 0), a3, voffA);
;             PG8_WAIT_V(8); PG8_WAIT_L(0); PG8_BAR; PG8_MMA(1, 0, At, B0); PG8_MMA(1, 1, At, B1); PG8_BAR; PG8_SCHED;
	s_add_i32 s4, s72, s54
	v_lshl_add_u64 v[212:213], v[212:213], 0, s[12:13]
	s_mov_b32 m0, s4
	ds_read_b128 v[160:163], v247 offset:49152
	ds_read_b128 v[164:167], v247 offset:50176
	ds_read_b128 v[168:171], v247 offset:51200
	ds_read_b128 v[172:175], v247 offset:52224
	ds_read_b128 v[176:179], v247 offset:53248
	ds_read_b128 v[180:183], v247 offset:54272
	ds_read_b128 v[184:187], v247 offset:55296
	ds_read_b128 v[188:191], v247 offset:56320
	global_load_lds_dwordx4 v[212:213], off
	v_lshl_add_u64 v[212:213], v[214:215], 0, s[12:13]
	s_add_i32 m0, s4, 0x2000
	s_add_i32 s4, s73, s54
	global_load_lds_dwordx4 v[212:213], off
	v_lshl_add_u64 v[212:213], v[216:217], 0, s[12:13]
	s_mov_b32 m0, s4
	s_nop 0
	global_load_lds_dwordx4 v[212:213], off
	v_lshl_add_u64 v[212:213], v[218:219], 0, s[12:13]
	s_add_i32 m0, s4, 0x2000
	s_nop 0
	global_load_lds_dwordx4 v[212:213], off
	v_lshl_add_u64 v[212:213], v[220:221], 0, s[12:13]
	s_mov_b32 m0, s59
	s_nop 0
	global_load_lds_dwordx4 v[212:213], off
	v_lshl_add_u64 v[212:213], v[222:223], 0, s[12:13]
	s_mov_b32 m0, s60
	s_nop 0
	global_load_lds_dwordx4 v[212:213], off
	s_waitcnt vmcnt(8)
	s_waitcnt lgkmcnt(0)
	v_mfma_f32_16x16x32_bf16 v[60:63], v[128:131], v[160:163], v[60:63]
	v_mfma_f32_16x16x32_bf16 v[56:59], v[136:139], v[160:163], v[56:59]
	v_mfma_f32_16x16x32_bf16 v[44:47], v[128:131], v[168:171], v[44:47]
	v_mfma_f32_16x16x32_bf16 v[40:43], v[136:139], v[168:171], v[40:43]
	v_mfma_f32_16x16x32_bf16 v[28:31], v[128:131], v[176:179], v[28:31]
	v_mfma_f32_16x16x32_bf16 v[24:27], v[136:139], v[176:179], v[24:27]
	s_barrier
	s_setprio 1
	s_waitcnt lgkmcnt(0)
	v_mfma_f32_16x16x32_bf16 v[12:15], v[128:131], v[184:187], v[12:15]
	v_mfma_f32_16x16x32_bf16 v[8:11], v[136:139], v[184:187], v[8:11]
	v_mfma_f32_16x16x32_bf16 v[60:63], v[132:135], v[164:167], v[60:63]
	v_mfma_f32_16x16x32_bf16 v[56:59], v[140:143], v[164:167], v[56:59]
	v_mfma_f32_16x16x32_bf16 v[44:47], v[132:135], v[172:175], v[44:47]
	v_mfma_f32_16x16x32_bf16 v[40:43], v[140:143], v[172:175], v[40:43]
	v_mfma_f32_16x16x32_bf16 v[28:31], v[132:135], v[180:183], v[28:31]
	v_mfma_f32_16x16x32_bf16 v[24:27], v[140:143], v[180:183], v[24:27]
	v_mfma_f32_16x16x32_bf16 v[12:15], v[132:135], v[188:191], v[12:15]
	v_mfma_f32_16x16x32_bf16 v[8:11], v[140:143], v[188:191], v[8:11]
	s_setprio 0
	s_setprio 1
	v_mfma_f32_16x16x32_bf16 v[52:55], v[144:147], v[160:163], v[52:55]
	v_mfma_f32_16x16x32_bf16 v[48:51], v[152:155], v[160:163], v[48:51]
	v_mfma_f32_16x16x32_bf16 v[36:39], v[144:147], v[168:171], v[36:39]
	v_mfma_f32_16x16x32_bf16 v[32:35], v[152:155], v[168:171], v[32:35]
	v_mfma_f32_16x16x32_bf16 v[20:23], v[144:147], v[176:179], v[20:23]
	v_mfma_f32_16x16x32_bf16 v[16:19], v[152:155], v[176:179], v[16:19]
	v_mfma_f32_16x16x32_bf16 v[4:7], v[144:147], v[184:187], v[4:7]
	v_mfma_f32_16x16x32_bf16 v[0:3], v[152:155], v[184:187], v[0:3]
	v_mfma_f32_16x16x32_bf16 v[52:55], v[148:151], v[164:167], v[52:55]
	v_mfma_f32_16x16x32_bf16 v[48:51], v[156:159], v[164:167], v[48:51]
	v_mfma_f32_16x16x32_bf16 v[36:39], v[148:151], v[172:175], v[36:39]
	v_mfma_f32_16x16x32_bf16 v[32:35], v[156:159], v[172:175], v[32:35]
	v_mfma_f32_16x16x32_bf16 v[20:23], v[148:151], v[180:183], v[20:23]
	v_mfma_f32_16x16x32_bf16 v[16:19], v[156:159], v[180:183], v[16:19]
	v_mfma_f32_16x16x32_bf16 v[4:7], v[148:151], v[188:191], v[4:7]
	v_mfma_f32_16x16x32_bf16 v[0:3], v[156:159], v[188:191], v[0:3]
	s_setprio 0
	s_barrier
	s_add_u32 s0, s0, 0x100
	s_addc_u32 s1, s1, 0
	s_add_u32 s6, s6, 0x100
	s_addc_u32 s7, s7, 0
	s_cmp_ge_u32 s71, s61
	s_mov_b32 s4, s71
	s_cbranch_scc0 .LBB0_222
